# gemm96 phase loop: next-chunk LDS-DMAs issued ahead of the MFMA groups (early issue) on top of v96
# speedup vs baseline: 1.0090x; 1.0090x over previous
.LBB1_82:
	s_lshl_b32 s19, s18, 8
	s_add_i32 s19, s19, 0x80
	s_min_u32 s19, s19, 0x780
	s_add_u32 s40, s8, s19
	s_addc_u32 s41, s9, 0
	s_add_u32 s42, s10, s19
	s_addc_u32 s43, s11, 0
	ds_read_b128 v[142:145], v234 offset:0
	ds_read_b128 v[146:149], v234 offset:2048
	ds_read_b128 v[150:153], v234 offset:4096
	ds_read_b128 v[154:157], v234 offset:6144
	ds_read_b128 v[130:133], v232 offset:0
	ds_read_b128 v[134:137], v232 offset:2048
	ds_read_b128 v[138:141], v232 offset:4096
	ds_read_b128 v[216:219], v235 offset:0
	ds_read_b128 v[220:223], v235 offset:2048
	ds_read_b128 v[224:227], v235 offset:4096
	ds_read_b128 v[228:231], v235 offset:6144
	ds_read_b128 v[188:191], v233 offset:0
	ds_read_b128 v[192:195], v233 offset:2048
	ds_read_b128 v[196:199], v233 offset:4096
	s_add_i32 m0, s16, 0x7010
	s_nop 0
	global_load_lds_dwordx4 v238, s[40:41]
	s_add_i32 m0, s16, 0x7410
	s_add_u32 s12, s40, 0x4000
	s_addc_u32 s13, s41, 0
	global_load_lds_dwordx4 v239, s[12:13]
	s_add_i32 m0, s16, 0x7810
	s_add_u32 s12, s40, 0x8000
	s_addc_u32 s13, s41, 0
	global_load_lds_dwordx4 v238, s[12:13]
	s_add_i32 m0, s17, 0xa010
	s_nop 0
	global_load_lds_dwordx4 v236, s[42:43]
	s_add_i32 m0, s17, 0xa410
	s_add_u32 s12, s42, 0x4000
	s_addc_u32 s13, s43, 0
	global_load_lds_dwordx4 v237, s[12:13]
	s_add_i32 m0, s17, 0xa810
	s_add_u32 s12, s42, 0x8000
	s_addc_u32 s13, s43, 0
	global_load_lds_dwordx4 v236, s[12:13]
	s_add_i32 m0, s17, 0xac10
	s_add_u32 s12, s42, 0xc000
	s_addc_u32 s13, s43, 0
	global_load_lds_dwordx4 v237, s[12:13]
	s_waitcnt lgkmcnt(9)
	v_mfma_f32_16x16x32_bf16 v[72:75], v[142:145], v[130:133], v[72:75]
	v_mfma_f32_16x16x32_bf16 v[68:71], v[146:149], v[130:133], v[68:71]
	v_mfma_f32_16x16x32_bf16 v[44:47], v[150:153], v[130:133], v[44:47]
	v_mfma_f32_16x16x32_bf16 v[32:35], v[154:157], v[130:133], v[32:35]
	s_waitcnt lgkmcnt(8)
	v_mfma_f32_16x16x32_bf16 v[28:31], v[142:145], v[134:137], v[28:31]
	v_mfma_f32_16x16x32_bf16 v[24:27], v[146:149], v[134:137], v[24:27]
	v_mfma_f32_16x16x32_bf16 v[20:23], v[150:153], v[134:137], v[20:23]
	v_mfma_f32_16x16x32_bf16 v[16:19], v[154:157], v[134:137], v[16:19]
	s_waitcnt lgkmcnt(7)
	v_mfma_f32_16x16x32_bf16 v[12:15], v[142:145], v[138:141], v[12:15]
	v_mfma_f32_16x16x32_bf16 v[8:11], v[146:149], v[138:141], v[8:11]
	v_mfma_f32_16x16x32_bf16 v[4:7], v[150:153], v[138:141], v[4:7]
	v_mfma_f32_16x16x32_bf16 v[0:3], v[154:157], v[138:141], v[0:3]
	s_waitcnt lgkmcnt(2)
	v_mfma_f32_16x16x32_bf16 v[72:75], v[216:219], v[188:191], v[72:75]
	v_mfma_f32_16x16x32_bf16 v[68:71], v[220:223], v[188:191], v[68:71]
	v_mfma_f32_16x16x32_bf16 v[44:47], v[224:227], v[188:191], v[44:47]
	v_mfma_f32_16x16x32_bf16 v[32:35], v[228:231], v[188:191], v[32:35]
	s_waitcnt lgkmcnt(1)
	v_mfma_f32_16x16x32_bf16 v[28:31], v[216:219], v[192:195], v[28:31]
	v_mfma_f32_16x16x32_bf16 v[24:27], v[220:223], v[192:195], v[24:27]
	v_mfma_f32_16x16x32_bf16 v[20:23], v[224:227], v[192:195], v[20:23]
	v_mfma_f32_16x16x32_bf16 v[16:19], v[228:231], v[192:195], v[16:19]
	s_waitcnt lgkmcnt(0)
	v_mfma_f32_16x16x32_bf16 v[12:15], v[216:219], v[196:199], v[12:15]
	v_mfma_f32_16x16x32_bf16 v[8:11], v[220:223], v[196:199], v[8:11]
	v_mfma_f32_16x16x32_bf16 v[4:7], v[224:227], v[196:199], v[4:7]
	v_mfma_f32_16x16x32_bf16 v[0:3], v[228:231], v[196:199], v[0:3]
	s_waitcnt vmcnt(0)
	s_barrier
	s_lshl_b32 s19, s18, 8
	s_add_i32 s19, s19, 0x100
	s_min_u32 s19, s19, 0x780
	s_add_u32 s40, s8, s19
	s_addc_u32 s41, s9, 0
	s_add_u32 s42, s10, s19
	s_addc_u32 s43, s11, 0
	ds_read_b128 v[142:145], v234 offset:28672
	ds_read_b128 v[146:149], v234 offset:30720
	ds_read_b128 v[150:153], v234 offset:32768
	ds_read_b128 v[154:157], v234 offset:34816
	ds_read_b128 v[130:133], v232 offset:28672
	ds_read_b128 v[134:137], v232 offset:30720
	ds_read_b128 v[138:141], v232 offset:32768
	ds_read_b128 v[216:219], v235 offset:28672
	ds_read_b128 v[220:223], v235 offset:30720
	ds_read_b128 v[224:227], v235 offset:32768
	ds_read_b128 v[228:231], v235 offset:34816
	ds_read_b128 v[188:191], v233 offset:28672
	ds_read_b128 v[192:195], v233 offset:30720
	ds_read_b128 v[196:199], v233 offset:32768
	s_add_i32 m0, s16, 0x10
	s_nop 0
	global_load_lds_dwordx4 v238, s[40:41]
	s_add_i32 m0, s16, 0x410
	s_add_u32 s12, s40, 0x4000
	s_addc_u32 s13, s41, 0
	global_load_lds_dwordx4 v239, s[12:13]
	s_add_i32 m0, s16, 0x810
	s_add_u32 s12, s40, 0x8000
	s_addc_u32 s13, s41, 0
	global_load_lds_dwordx4 v238, s[12:13]
	s_add_i32 m0, s17, 0x3010
	s_nop 0
	global_load_lds_dwordx4 v236, s[42:43]
	s_add_i32 m0, s17, 0x3410
	s_add_u32 s12, s42, 0x4000
	s_addc_u32 s13, s43, 0
	global_load_lds_dwordx4 v237, s[12:13]
	s_add_i32 m0, s17, 0x3810
	s_add_u32 s12, s42, 0x8000
	s_addc_u32 s13, s43, 0
	global_load_lds_dwordx4 v236, s[12:13]
	s_add_i32 m0, s17, 0x3c10
	s_add_u32 s12, s42, 0xc000
	s_addc_u32 s13, s43, 0
	global_load_lds_dwordx4 v237, s[12:13]
	s_waitcnt lgkmcnt(9)
	v_mfma_f32_16x16x32_bf16 v[72:75], v[142:145], v[130:133], v[72:75]
	v_mfma_f32_16x16x32_bf16 v[68:71], v[146:149], v[130:133], v[68:71]
	v_mfma_f32_16x16x32_bf16 v[44:47], v[150:153], v[130:133], v[44:47]
	v_mfma_f32_16x16x32_bf16 v[32:35], v[154:157], v[130:133], v[32:35]
	s_waitcnt lgkmcnt(8)
	v_mfma_f32_16x16x32_bf16 v[28:31], v[142:145], v[134:137], v[28:31]
	v_mfma_f32_16x16x32_bf16 v[24:27], v[146:149], v[134:137], v[24:27]
	v_mfma_f32_16x16x32_bf16 v[20:23], v[150:153], v[134:137], v[20:23]
	v_mfma_f32_16x16x32_bf16 v[16:19], v[154:157], v[134:137], v[16:19]
	s_waitcnt lgkmcnt(7)
	v_mfma_f32_16x16x32_bf16 v[12:15], v[142:145], v[138:141], v[12:15]
	v_mfma_f32_16x16x32_bf16 v[8:11], v[146:149], v[138:141], v[8:11]
	v_mfma_f32_16x16x32_bf16 v[4:7], v[150:153], v[138:141], v[4:7]
	v_mfma_f32_16x16x32_bf16 v[0:3], v[154:157], v[138:141], v[0:3]
	s_waitcnt lgkmcnt(2)
	v_mfma_f32_16x16x32_bf16 v[72:75], v[216:219], v[188:191], v[72:75]
	v_mfma_f32_16x16x32_bf16 v[68:71], v[220:223], v[188:191], v[68:71]
	v_mfma_f32_16x16x32_bf16 v[44:47], v[224:227], v[188:191], v[44:47]
	v_mfma_f32_16x16x32_bf16 v[32:35], v[228:231], v[188:191], v[32:35]
	s_waitcnt lgkmcnt(1)
	v_mfma_f32_16x16x32_bf16 v[28:31], v[216:219], v[192:195], v[28:31]
	v_mfma_f32_16x16x32_bf16 v[24:27], v[220:223], v[192:195], v[24:27]
	v_mfma_f32_16x16x32_bf16 v[20:23], v[224:227], v[192:195], v[20:23]
	v_mfma_f32_16x16x32_bf16 v[16:19], v[228:231], v[192:195], v[16:19]
	s_waitcnt lgkmcnt(0)
	v_mfma_f32_16x16x32_bf16 v[12:15], v[216:219], v[196:199], v[12:15]
	v_mfma_f32_16x16x32_bf16 v[8:11], v[220:223], v[196:199], v[8:11]
	v_mfma_f32_16x16x32_bf16 v[4:7], v[224:227], v[196:199], v[4:7]
	v_mfma_f32_16x16x32_bf16 v[0:3], v[228:231], v[196:199], v[0:3]
	s_waitcnt vmcnt(0)
	s_barrier
	s_add_i32 s18, s18, 1
	s_cmp_eq_u32 s18, 8
	s_cbranch_scc0 .LBB1_82
	s_setprio 0
	s_waitcnt vmcnt(0)
	v_readlane_b32 s14, v242, 0
	s_add_i32 s15, s2, 1
	s_lshl_b32 s15, s15, 3
	s_and_b32 s24, s14, 7
	s_or_b32 s15, s15, s24
	s_mul_i32 s15, s15, s55
	s_lshr_b32 s14, s14, 3
	s_add_i32 s15, s15, s14
	s_cmp_lt_u32 s15, 0x580
	s_cselect_b32 s59, 1, 0
	s_cbranch_scc0 .Lg96pf_none_g3
	s_lshr_b32 s14, s15, 6
	s_lshl_b32 s14, s14, 3
	s_and_b32 s24, s15, 7
	s_add_i32 s14, s14, s24
	s_mul_i32 s14, s14, 96
	s_sub_i32 s14, s14, s5
	s_bfe_u32 s24, s15, 0x30003
	s_lshl_b32 s24, s24, 7
	s_sub_i32 s24, s24, s4
	s_ashr_i32 s15, s14, 31
	s_lshl_b64 s[14:15], s[14:15], 11
	s_add_u32 s88, s8, s14
	s_addc_u32 s89, s9, s15
	s_ashr_i32 s25, s24, 31
	s_lshl_b64 s[24:25], s[24:25], 11
	s_add_u32 s90, s10, s24
	s_addc_u32 s91, s11, s25
	s_add_i32 m0, s16, 0x10
	s_nop 0
	global_load_lds_dwordx4 v238, s[88:89]
	s_add_i32 m0, s16, 0x410
	s_add_u32 s14, s88, 0x4000
	s_addc_u32 s15, s89, 0
	global_load_lds_dwordx4 v239, s[14:15]
	s_add_i32 m0, s16, 0x810
	s_add_u32 s14, s88, 0x8000
	s_addc_u32 s15, s89, 0
	global_load_lds_dwordx4 v238, s[14:15]
	s_add_i32 m0, s17, 0x3010
	s_nop 0
	global_load_lds_dwordx4 v236, s[90:91]
	s_add_i32 m0, s17, 0x3410
	s_add_u32 s14, s90, 0x4000
	s_addc_u32 s15, s91, 0
	global_load_lds_dwordx4 v237, s[14:15]
	s_add_i32 m0, s17, 0x3810
	s_add_u32 s14, s90, 0x8000
	s_addc_u32 s15, s91, 0
	global_load_lds_dwordx4 v236, s[14:15]
	s_add_i32 m0, s17, 0x3c10
	s_add_u32 s14, s90, 0xc000
	s_addc_u32 s15, s91, 0
	global_load_lds_dwordx4 v237, s[14:15]

.LBB1_90:
	s_lshl_b32 s19, s18, 8
	s_add_i32 s19, s19, 0x80
	s_min_u32 s19, s19, 0x780
	s_add_u32 s40, s8, s19
	s_addc_u32 s41, s9, 0
	s_add_u32 s42, s10, s19
	s_addc_u32 s43, s11, 0
	ds_read_b128 v[142:145], v234 offset:0
	ds_read_b128 v[146:149], v234 offset:2048
	ds_read_b128 v[150:153], v234 offset:4096
	ds_read_b128 v[154:157], v234 offset:6144
	ds_read_b128 v[130:133], v232 offset:0
	ds_read_b128 v[134:137], v232 offset:2048
	ds_read_b128 v[138:141], v232 offset:4096
	ds_read_b128 v[216:219], v235 offset:0
	ds_read_b128 v[220:223], v235 offset:2048
	ds_read_b128 v[224:227], v235 offset:4096
	ds_read_b128 v[228:231], v235 offset:6144
	ds_read_b128 v[188:191], v233 offset:0
	ds_read_b128 v[192:195], v233 offset:2048
	ds_read_b128 v[196:199], v233 offset:4096
	s_add_i32 m0, s16, 0x7010
	s_nop 0
	global_load_lds_dwordx4 v238, s[40:41]
	s_add_i32 m0, s16, 0x7410
	s_add_u32 s12, s40, 0x4000
	s_addc_u32 s13, s41, 0
	global_load_lds_dwordx4 v239, s[12:13]
	s_add_i32 m0, s16, 0x7810
	s_add_u32 s12, s40, 0x8000
	s_addc_u32 s13, s41, 0
	global_load_lds_dwordx4 v238, s[12:13]
	s_add_i32 m0, s17, 0xa010
	s_nop 0
	global_load_lds_dwordx4 v236, s[42:43]
	s_add_i32 m0, s17, 0xa410
	s_add_u32 s12, s42, 0x4000
	s_addc_u32 s13, s43, 0
	global_load_lds_dwordx4 v237, s[12:13]
	s_add_i32 m0, s17, 0xa810
	s_add_u32 s12, s42, 0x8000
	s_addc_u32 s13, s43, 0
	global_load_lds_dwordx4 v236, s[12:13]
	s_add_i32 m0, s17, 0xac10
	s_add_u32 s12, s42, 0xc000
	s_addc_u32 s13, s43, 0
	global_load_lds_dwordx4 v237, s[12:13]
	s_waitcnt lgkmcnt(9)
	v_mfma_f32_16x16x32_bf16 v[72:75], v[142:145], v[130:133], v[72:75]
	v_mfma_f32_16x16x32_bf16 v[40:43], v[146:149], v[130:133], v[40:43]
	v_mfma_f32_16x16x32_bf16 v[36:39], v[150:153], v[130:133], v[36:39]
	v_mfma_f32_16x16x32_bf16 v[32:35], v[154:157], v[130:133], v[32:35]
	s_waitcnt lgkmcnt(8)
	v_mfma_f32_16x16x32_bf16 v[28:31], v[142:145], v[134:137], v[28:31]
	v_mfma_f32_16x16x32_bf16 v[24:27], v[146:149], v[134:137], v[24:27]
	v_mfma_f32_16x16x32_bf16 v[20:23], v[150:153], v[134:137], v[20:23]
	v_mfma_f32_16x16x32_bf16 v[16:19], v[154:157], v[134:137], v[16:19]
	s_waitcnt lgkmcnt(7)
	v_mfma_f32_16x16x32_bf16 v[12:15], v[142:145], v[138:141], v[12:15]
	v_mfma_f32_16x16x32_bf16 v[8:11], v[146:149], v[138:141], v[8:11]
	v_mfma_f32_16x16x32_bf16 v[4:7], v[150:153], v[138:141], v[4:7]
	v_mfma_f32_16x16x32_bf16 v[0:3], v[154:157], v[138:141], v[0:3]
	s_waitcnt lgkmcnt(2)
	v_mfma_f32_16x16x32_bf16 v[72:75], v[216:219], v[188:191], v[72:75]
	v_mfma_f32_16x16x32_bf16 v[40:43], v[220:223], v[188:191], v[40:43]
	v_mfma_f32_16x16x32_bf16 v[36:39], v[224:227], v[188:191], v[36:39]
	v_mfma_f32_16x16x32_bf16 v[32:35], v[228:231], v[188:191], v[32:35]
	s_waitcnt lgkmcnt(1)
	v_mfma_f32_16x16x32_bf16 v[28:31], v[216:219], v[192:195], v[28:31]
	v_mfma_f32_16x16x32_bf16 v[24:27], v[220:223], v[192:195], v[24:27]
	v_mfma_f32_16x16x32_bf16 v[20:23], v[224:227], v[192:195], v[20:23]
	v_mfma_f32_16x16x32_bf16 v[16:19], v[228:231], v[192:195], v[16:19]
	s_waitcnt lgkmcnt(0)
	v_mfma_f32_16x16x32_bf16 v[12:15], v[216:219], v[196:199], v[12:15]
	v_mfma_f32_16x16x32_bf16 v[8:11], v[220:223], v[196:199], v[8:11]
	v_mfma_f32_16x16x32_bf16 v[4:7], v[224:227], v[196:199], v[4:7]
	v_mfma_f32_16x16x32_bf16 v[0:3], v[228:231], v[196:199], v[0:3]
	s_waitcnt vmcnt(0)
	s_barrier
	s_lshl_b32 s19, s18, 8
	s_add_i32 s19, s19, 0x100
	s_min_u32 s19, s19, 0x780
	s_add_u32 s40, s8, s19
	s_addc_u32 s41, s9, 0
	s_add_u32 s42, s10, s19
	s_addc_u32 s43, s11, 0
	ds_read_b128 v[142:145], v234 offset:28672
	ds_read_b128 v[146:149], v234 offset:30720
	ds_read_b128 v[150:153], v234 offset:32768
	ds_read_b128 v[154:157], v234 offset:34816
	ds_read_b128 v[130:133], v232 offset:28672
	ds_read_b128 v[134:137], v232 offset:30720
	ds_read_b128 v[138:141], v232 offset:32768
	ds_read_b128 v[216:219], v235 offset:28672
	ds_read_b128 v[220:223], v235 offset:30720
	ds_read_b128 v[224:227], v235 offset:32768
	ds_read_b128 v[228:231], v235 offset:34816
	ds_read_b128 v[188:191], v233 offset:28672
	ds_read_b128 v[192:195], v233 offset:30720
	ds_read_b128 v[196:199], v233 offset:32768
	s_add_i32 m0, s16, 0x10
	s_nop 0
	global_load_lds_dwordx4 v238, s[40:41]
	s_add_i32 m0, s16, 0x410
	s_add_u32 s12, s40, 0x4000
	s_addc_u32 s13, s41, 0
	global_load_lds_dwordx4 v239, s[12:13]
	s_add_i32 m0, s16, 0x810
	s_add_u32 s12, s40, 0x8000
	s_addc_u32 s13, s41, 0
	global_load_lds_dwordx4 v238, s[12:13]
	s_add_i32 m0, s17, 0x3010
	s_nop 0
	global_load_lds_dwordx4 v236, s[42:43]
	s_add_i32 m0, s17, 0x3410
	s_add_u32 s12, s42, 0x4000
	s_addc_u32 s13, s43, 0
	global_load_lds_dwordx4 v237, s[12:13]
	s_add_i32 m0, s17, 0x3810
	s_add_u32 s12, s42, 0x8000
	s_addc_u32 s13, s43, 0
	global_load_lds_dwordx4 v236, s[12:13]
	s_add_i32 m0, s17, 0x3c10
	s_add_u32 s12, s42, 0xc000
	s_addc_u32 s13, s43, 0
	global_load_lds_dwordx4 v237, s[12:13]
	s_waitcnt lgkmcnt(9)
	v_mfma_f32_16x16x32_bf16 v[72:75], v[142:145], v[130:133], v[72:75]
	v_mfma_f32_16x16x32_bf16 v[40:43], v[146:149], v[130:133], v[40:43]
	v_mfma_f32_16x16x32_bf16 v[36:39], v[150:153], v[130:133], v[36:39]
	v_mfma_f32_16x16x32_bf16 v[32:35], v[154:157], v[130:133], v[32:35]
	s_waitcnt lgkmcnt(8)
	v_mfma_f32_16x16x32_bf16 v[28:31], v[142:145], v[134:137], v[28:31]
	v_mfma_f32_16x16x32_bf16 v[24:27], v[146:149], v[134:137], v[24:27]
	v_mfma_f32_16x16x32_bf16 v[20:23], v[150:153], v[134:137], v[20:23]
	v_mfma_f32_16x16x32_bf16 v[16:19], v[154:157], v[134:137], v[16:19]
	s_waitcnt lgkmcnt(7)
	v_mfma_f32_16x16x32_bf16 v[12:15], v[142:145], v[138:141], v[12:15]
	v_mfma_f32_16x16x32_bf16 v[8:11], v[146:149], v[138:141], v[8:11]
	v_mfma_f32_16x16x32_bf16 v[4:7], v[150:153], v[138:141], v[4:7]
	v_mfma_f32_16x16x32_bf16 v[0:3], v[154:157], v[138:141], v[0:3]
	s_waitcnt lgkmcnt(2)
	v_mfma_f32_16x16x32_bf16 v[72:75], v[216:219], v[188:191], v[72:75]
	v_mfma_f32_16x16x32_bf16 v[40:43], v[220:223], v[188:191], v[40:43]
	v_mfma_f32_16x16x32_bf16 v[36:39], v[224:227], v[188:191], v[36:39]
	v_mfma_f32_16x16x32_bf16 v[32:35], v[228:231], v[188:191], v[32:35]
	s_waitcnt lgkmcnt(1)
	v_mfma_f32_16x16x32_bf16 v[28:31], v[216:219], v[192:195], v[28:31]
	v_mfma_f32_16x16x32_bf16 v[24:27], v[220:223], v[192:195], v[24:27]
	v_mfma_f32_16x16x32_bf16 v[20:23], v[224:227], v[192:195], v[20:23]
	v_mfma_f32_16x16x32_bf16 v[16:19], v[228:231], v[192:195], v[16:19]
	s_waitcnt lgkmcnt(0)
	v_mfma_f32_16x16x32_bf16 v[12:15], v[216:219], v[196:199], v[12:15]
	v_mfma_f32_16x16x32_bf16 v[8:11], v[220:223], v[196:199], v[8:11]
	v_mfma_f32_16x16x32_bf16 v[4:7], v[224:227], v[196:199], v[4:7]
	v_mfma_f32_16x16x32_bf16 v[0:3], v[228:231], v[196:199], v[0:3]
	s_waitcnt vmcnt(0)
	s_barrier
	s_add_i32 s18, s18, 1
	s_cmp_eq_u32 s18, 8
	s_cbranch_scc0 .LBB1_90
	s_setprio 0
	s_waitcnt vmcnt(0)
	v_readlane_b32 s14, v242, 0
	s_add_i32 s15, s2, 1
	s_lshl_b32 s15, s15, 3
	s_and_b32 s24, s14, 7
	s_or_b32 s15, s15, s24
	s_mul_i32 s15, s15, s55
	s_lshr_b32 s14, s14, 3
	s_add_i32 s15, s15, s14
	s_cmp_lt_u32 s15, 0x580
	s_cselect_b32 s59, 1, 0
	s_cbranch_scc0 .Lg96pf_none_g2a
	s_lshr_b32 s14, s15, 6
	s_lshl_b32 s14, s14, 3
	s_and_b32 s24, s15, 7
	s_add_i32 s14, s14, s24
	s_mul_i32 s14, s14, 96
	s_sub_i32 s14, s14, s5
	s_bfe_u32 s24, s15, 0x30003
	s_lshl_b32 s24, s24, 7
	s_sub_i32 s24, s24, s4
	s_ashr_i32 s15, s14, 31
	s_lshl_b64 s[14:15], s[14:15], 11
	s_add_u32 s88, s8, s14
	s_addc_u32 s89, s9, s15
	s_ashr_i32 s25, s24, 31
	s_lshl_b64 s[24:25], s[24:25], 11
	s_add_u32 s90, s10, s24
	s_addc_u32 s91, s11, s25
	s_add_i32 m0, s16, 0x10
	s_nop 0
	global_load_lds_dwordx4 v238, s[88:89]
	s_add_i32 m0, s16, 0x410
	s_add_u32 s14, s88, 0x4000
	s_addc_u32 s15, s89, 0
	global_load_lds_dwordx4 v239, s[14:15]
	s_add_i32 m0, s16, 0x810
	s_add_u32 s14, s88, 0x8000
	s_addc_u32 s15, s89, 0
	global_load_lds_dwordx4 v238, s[14:15]
	s_add_i32 m0, s17, 0x3010
	s_nop 0
	global_load_lds_dwordx4 v236, s[90:91]
	s_add_i32 m0, s17, 0x3410
	s_add_u32 s14, s90, 0x4000
	s_addc_u32 s15, s91, 0
	global_load_lds_dwordx4 v237, s[14:15]
	s_add_i32 m0, s17, 0x3810
	s_add_u32 s14, s90, 0x8000
	s_addc_u32 s15, s91, 0
	global_load_lds_dwordx4 v236, s[14:15]
	s_add_i32 m0, s17, 0x3c10
	s_add_u32 s14, s90, 0xc000
	s_addc_u32 s15, s91, 0
	global_load_lds_dwordx4 v237, s[14:15]

.LBB1_808:
	s_lshl_b32 s19, s18, 8
	s_add_i32 s19, s19, 0x80
	s_min_u32 s19, s19, 0x780
	s_add_u32 s40, s8, s19
	s_addc_u32 s41, s9, 0
	s_add_u32 s42, s10, s19
	s_addc_u32 s43, s11, 0
	ds_read_b128 v[142:145], v234 offset:0
	ds_read_b128 v[146:149], v234 offset:2048
	ds_read_b128 v[150:153], v234 offset:4096
	ds_read_b128 v[154:157], v234 offset:6144
	ds_read_b128 v[130:133], v232 offset:0
	ds_read_b128 v[134:137], v232 offset:2048
	ds_read_b128 v[138:141], v232 offset:4096
	ds_read_b128 v[216:219], v235 offset:0
	ds_read_b128 v[220:223], v235 offset:2048
	ds_read_b128 v[224:227], v235 offset:4096
	ds_read_b128 v[228:231], v235 offset:6144
	ds_read_b128 v[188:191], v233 offset:0
	ds_read_b128 v[192:195], v233 offset:2048
	ds_read_b128 v[196:199], v233 offset:4096
	s_add_i32 m0, s16, 0x7010
	s_nop 0
	global_load_lds_dwordx4 v238, s[40:41]
	s_add_i32 m0, s16, 0x7410
	s_add_u32 s12, s40, 0x4000
	s_addc_u32 s13, s41, 0
	global_load_lds_dwordx4 v239, s[12:13]
	s_add_i32 m0, s16, 0x7810
	s_add_u32 s12, s40, 0x8000
	s_addc_u32 s13, s41, 0
	global_load_lds_dwordx4 v238, s[12:13]
	s_add_i32 m0, s17, 0xa010
	s_nop 0
	global_load_lds_dwordx4 v236, s[42:43]
	s_add_i32 m0, s17, 0xa410
	s_add_u32 s12, s42, 0x4000
	s_addc_u32 s13, s43, 0
	global_load_lds_dwordx4 v237, s[12:13]
	s_add_i32 m0, s17, 0xa810
	s_add_u32 s12, s42, 0x8000
	s_addc_u32 s13, s43, 0
	global_load_lds_dwordx4 v236, s[12:13]
	s_add_i32 m0, s17, 0xac10
	s_add_u32 s12, s42, 0xc000
	s_addc_u32 s13, s43, 0
	global_load_lds_dwordx4 v237, s[12:13]
	s_waitcnt lgkmcnt(9)
	v_mfma_f32_16x16x32_bf16 v[72:75], v[142:145], v[130:133], v[72:75]
	v_mfma_f32_16x16x32_bf16 v[40:43], v[146:149], v[130:133], v[40:43]
	v_mfma_f32_16x16x32_bf16 v[36:39], v[150:153], v[130:133], v[36:39]
	v_mfma_f32_16x16x32_bf16 v[32:35], v[154:157], v[130:133], v[32:35]
	s_waitcnt lgkmcnt(8)
	v_mfma_f32_16x16x32_bf16 v[28:31], v[142:145], v[134:137], v[28:31]
	v_mfma_f32_16x16x32_bf16 v[24:27], v[146:149], v[134:137], v[24:27]
	v_mfma_f32_16x16x32_bf16 v[20:23], v[150:153], v[134:137], v[20:23]
	v_mfma_f32_16x16x32_bf16 v[16:19], v[154:157], v[134:137], v[16:19]
	s_waitcnt lgkmcnt(7)
	v_mfma_f32_16x16x32_bf16 v[12:15], v[142:145], v[138:141], v[12:15]
	v_mfma_f32_16x16x32_bf16 v[8:11], v[146:149], v[138:141], v[8:11]
	v_mfma_f32_16x16x32_bf16 v[4:7], v[150:153], v[138:141], v[4:7]
	v_mfma_f32_16x16x32_bf16 v[0:3], v[154:157], v[138:141], v[0:3]
	s_waitcnt lgkmcnt(2)
	v_mfma_f32_16x16x32_bf16 v[72:75], v[216:219], v[188:191], v[72:75]
	v_mfma_f32_16x16x32_bf16 v[40:43], v[220:223], v[188:191], v[40:43]
	v_mfma_f32_16x16x32_bf16 v[36:39], v[224:227], v[188:191], v[36:39]
	v_mfma_f32_16x16x32_bf16 v[32:35], v[228:231], v[188:191], v[32:35]
	s_waitcnt lgkmcnt(1)
	v_mfma_f32_16x16x32_bf16 v[28:31], v[216:219], v[192:195], v[28:31]
	v_mfma_f32_16x16x32_bf16 v[24:27], v[220:223], v[192:195], v[24:27]
	v_mfma_f32_16x16x32_bf16 v[20:23], v[224:227], v[192:195], v[20:23]
	v_mfma_f32_16x16x32_bf16 v[16:19], v[228:231], v[192:195], v[16:19]
	s_waitcnt lgkmcnt(0)
	v_mfma_f32_16x16x32_bf16 v[12:15], v[216:219], v[196:199], v[12:15]
	v_mfma_f32_16x16x32_bf16 v[8:11], v[220:223], v[196:199], v[8:11]
	v_mfma_f32_16x16x32_bf16 v[4:7], v[224:227], v[196:199], v[4:7]
	v_mfma_f32_16x16x32_bf16 v[0:3], v[228:231], v[196:199], v[0:3]
	s_waitcnt vmcnt(0)
	s_barrier
	s_lshl_b32 s19, s18, 8
	s_add_i32 s19, s19, 0x100
	s_min_u32 s19, s19, 0x780
	s_add_u32 s40, s8, s19
	s_addc_u32 s41, s9, 0
	s_add_u32 s42, s10, s19
	s_addc_u32 s43, s11, 0
	ds_read_b128 v[142:145], v234 offset:28672
	ds_read_b128 v[146:149], v234 offset:30720
	ds_read_b128 v[150:153], v234 offset:32768
	ds_read_b128 v[154:157], v234 offset:34816
	ds_read_b128 v[130:133], v232 offset:28672
	ds_read_b128 v[134:137], v232 offset:30720
	ds_read_b128 v[138:141], v232 offset:32768
	ds_read_b128 v[216:219], v235 offset:28672
	ds_read_b128 v[220:223], v235 offset:30720
	ds_read_b128 v[224:227], v235 offset:32768
	ds_read_b128 v[228:231], v235 offset:34816
	ds_read_b128 v[188:191], v233 offset:28672
	ds_read_b128 v[192:195], v233 offset:30720
	ds_read_b128 v[196:199], v233 offset:32768
	s_add_i32 m0, s16, 0x10
	s_nop 0
	global_load_lds_dwordx4 v238, s[40:41]
	s_add_i32 m0, s16, 0x410
	s_add_u32 s12, s40, 0x4000
	s_addc_u32 s13, s41, 0
	global_load_lds_dwordx4 v239, s[12:13]
	s_add_i32 m0, s16, 0x810
	s_add_u32 s12, s40, 0x8000
	s_addc_u32 s13, s41, 0
	global_load_lds_dwordx4 v238, s[12:13]
	s_add_i32 m0, s17, 0x3010
	s_nop 0
	global_load_lds_dwordx4 v236, s[42:43]
	s_add_i32 m0, s17, 0x3410
	s_add_u32 s12, s42, 0x4000
	s_addc_u32 s13, s43, 0
	global_load_lds_dwordx4 v237, s[12:13]
	s_add_i32 m0, s17, 0x3810
	s_add_u32 s12, s42, 0x8000
	s_addc_u32 s13, s43, 0
	global_load_lds_dwordx4 v236, s[12:13]
	s_add_i32 m0, s17, 0x3c10
	s_add_u32 s12, s42, 0xc000
	s_addc_u32 s13, s43, 0
	global_load_lds_dwordx4 v237, s[12:13]
	s_waitcnt lgkmcnt(9)
	v_mfma_f32_16x16x32_bf16 v[72:75], v[142:145], v[130:133], v[72:75]
	v_mfma_f32_16x16x32_bf16 v[40:43], v[146:149], v[130:133], v[40:43]
	v_mfma_f32_16x16x32_bf16 v[36:39], v[150:153], v[130:133], v[36:39]
	v_mfma_f32_16x16x32_bf16 v[32:35], v[154:157], v[130:133], v[32:35]
	s_waitcnt lgkmcnt(8)
	v_mfma_f32_16x16x32_bf16 v[28:31], v[142:145], v[134:137], v[28:31]
	v_mfma_f32_16x16x32_bf16 v[24:27], v[146:149], v[134:137], v[24:27]
	v_mfma_f32_16x16x32_bf16 v[20:23], v[150:153], v[134:137], v[20:23]
	v_mfma_f32_16x16x32_bf16 v[16:19], v[154:157], v[134:137], v[16:19]
	s_waitcnt lgkmcnt(7)
	v_mfma_f32_16x16x32_bf16 v[12:15], v[142:145], v[138:141], v[12:15]
	v_mfma_f32_16x16x32_bf16 v[8:11], v[146:149], v[138:141], v[8:11]
	v_mfma_f32_16x16x32_bf16 v[4:7], v[150:153], v[138:141], v[4:7]
	v_mfma_f32_16x16x32_bf16 v[0:3], v[154:157], v[138:141], v[0:3]
	s_waitcnt lgkmcnt(2)
	v_mfma_f32_16x16x32_bf16 v[72:75], v[216:219], v[188:191], v[72:75]
	v_mfma_f32_16x16x32_bf16 v[40:43], v[220:223], v[188:191], v[40:43]
	v_mfma_f32_16x16x32_bf16 v[36:39], v[224:227], v[188:191], v[36:39]
	v_mfma_f32_16x16x32_bf16 v[32:35], v[228:231], v[188:191], v[32:35]
	s_waitcnt lgkmcnt(1)
	v_mfma_f32_16x16x32_bf16 v[28:31], v[216:219], v[192:195], v[28:31]
	v_mfma_f32_16x16x32_bf16 v[24:27], v[220:223], v[192:195], v[24:27]
	v_mfma_f32_16x16x32_bf16 v[20:23], v[224:227], v[192:195], v[20:23]
	v_mfma_f32_16x16x32_bf16 v[16:19], v[228:231], v[192:195], v[16:19]
	s_waitcnt lgkmcnt(0)
	v_mfma_f32_16x16x32_bf16 v[12:15], v[216:219], v[196:199], v[12:15]
	v_mfma_f32_16x16x32_bf16 v[8:11], v[220:223], v[196:199], v[8:11]
	v_mfma_f32_16x16x32_bf16 v[4:7], v[224:227], v[196:199], v[4:7]
	v_mfma_f32_16x16x32_bf16 v[0:3], v[228:231], v[196:199], v[0:3]
	s_waitcnt vmcnt(0)
	s_barrier
	s_add_i32 s18, s18, 1
	s_cmp_eq_u32 s18, 8
	s_cbranch_scc0 .LBB1_808
	s_setprio 0
	s_waitcnt vmcnt(0)
	v_readlane_b32 s30, v242, 63
	s_nop 1
	s_add_i32 s31, s2, s30
	s_cmp_lt_u32 s31, 0x580
	s_cselect_b32 s59, 1, 0
	s_cbranch_scc0 .Lg96pf_none_g2b
	s_mul_i32 s38, s31, 745
	s_lshr_b32 s38, s38, 17
	s_mul_i32 s39, s38, 176
	s_sub_i32 s39, s31, s39
	s_mul_i32 s30, s39, 96
	s_sub_i32 s30, s30, s5
	s_ashr_i32 s31, s30, 31
	s_lshl_b64 s[30:31], s[30:31], 11
	s_add_u32 s88, s8, s30
	s_addc_u32 s89, s9, s31
	s_lshl_b32 s24, s38, 7
	s_sub_i32 s24, s24, s4
	s_ashr_i32 s25, s24, 31
	s_lshl_b64 s[24:25], s[24:25], 11
	s_add_u32 s90, s10, s24
	s_addc_u32 s91, s11, s25
	s_add_i32 m0, s16, 0x10
	s_nop 0
	global_load_lds_dwordx4 v238, s[88:89]
	s_add_i32 m0, s16, 0x410
	s_add_u32 s30, s88, 0x4000
	s_addc_u32 s31, s89, 0
	global_load_lds_dwordx4 v239, s[30:31]
	s_add_i32 m0, s16, 0x810
	s_add_u32 s30, s88, 0x8000
	s_addc_u32 s31, s89, 0
	global_load_lds_dwordx4 v238, s[30:31]
	s_add_i32 m0, s17, 0x3010
	s_nop 0
	global_load_lds_dwordx4 v236, s[90:91]
	s_add_i32 m0, s17, 0x3410
	s_add_u32 s30, s90, 0x4000
	s_addc_u32 s31, s91, 0
	global_load_lds_dwordx4 v237, s[30:31]
	s_add_i32 m0, s17, 0x3810
	s_add_u32 s30, s90, 0x8000
	s_addc_u32 s31, s91, 0
	global_load_lds_dwordx4 v236, s[30:31]
	s_add_i32 m0, s17, 0x3c10
	s_add_u32 s30, s90, 0xc000
	s_addc_u32 s31, s91, 0
	global_load_lds_dwordx4 v237, s[30:31]
